# v12 + per-CU start skew (0..3 x 1.1us by blockIdx>>3) in G1/G3 phases to de-synchronise tile store bursts
# speedup vs baseline: 1.0221x; 1.0045x over previous
; template <int EPI>
; __device__ __forceinline__ void gemm_phase256(const bf16_t* A, const bf16_t* Bt, int K, int NT, char* smem, void* outp, int ldo, int nvalid) {
;   constexpr int TM = (R + 255) / 256;
;   const int ntiles = TM * NT;
;   const int nb = gridDim.x;
;   const int xcd = blockIdx.x & 7, slot = blockIdx.x >> 3, per = nb >> 3;
;   for (int it = 0; it * nb < ntiles; ++it) {
;     const int k = (it * 8 + xcd) * per + slot;
;     if (k >= ntiles) continue;
;     const int panel = k / (TM * 8);
;     const int w = min(8, NT - panel * 8);
;     const int idx = k - panel * TM * 8;
;     const int tm = idx / w, tn = panel * 8 + idx % w;
;     gemm_tile8p<EPI>(A, Bt, K, K >> 6, tm * 256, tn * 256, smem, outp, ldo, nvalid, tm * 256, R - tm * 256);
;   }
.LBB0_166:
	s_and_b64 vcc, exec, s[2:3]
	s_cbranch_vccz .LBB0_241
	s_mov_b32 s10, 0
	s_lshr_b32 s2, s89, 3
	s_and_b32 s2, s2, 3
	s_cmp_eq_u32 s2, 0
	s_cbranch_scc1 .Lskew_done_g3
.Lskew_loop_g3:
	s_sleep 36
	s_add_i32 s2, s2, -1
	s_cmp_lg_u32 s2, 0
	s_cbranch_scc1 .Lskew_loop_g3
.Lskew_done_g3:
	s_branch .LBB0_170
.LBB0_168:
	s_or_b64 exec, exec, s[2:3]
	s_waitcnt vmcnt(0) lgkmcnt(0)
	s_barrier

; template <int EPI>
; __device__ __forceinline__ void gemm_phase256(const bf16_t* A, const bf16_t* Bt, int K, int NT, char* smem, void* outp, int ldo, int nvalid) {
;   constexpr int TM = (R + 255) / 256;
;   const int ntiles = TM * NT;
;   const int nb = gridDim.x;
;   const int xcd = blockIdx.x & 7, slot = blockIdx.x >> 3, per = nb >> 3;
;   for (int it = 0; it * nb < ntiles; ++it) {
;     const int k = (it * 8 + xcd) * per + slot;
;     if (k >= ntiles) continue;
;     const int panel = k / (TM * 8);
;     const int w = min(8, NT - panel * 8);
;     const int idx = k - panel * TM * 8;
;     const int tm = idx / w, tn = panel * 8 + idx % w;
;     gemm_tile8p<EPI>(A, Bt, K, K >> 6, tm * 256, tn * 256, smem, outp, ldo, nvalid, tm * 256, R - tm * 256);
;   }
.LBB0_1058:
	s_and_b64 vcc, exec, s[2:3]
	s_cbranch_vccz .LBB0_1325
	s_mov_b32 s10, 0
	s_waitcnt vmcnt(0)
	s_lshr_b32 s2, s89, 3
	s_and_b32 s2, s2, 3
	s_cmp_eq_u32 s2, 0
	s_cbranch_scc1 .Lskew_done_g1

; template <int EPI>
; __device__ __forceinline__ void gemm_phase256(const bf16_t* A, const bf16_t* Bt, int K, int NT, char* smem, void* outp, int ldo, int nvalid) {
;   constexpr int TM = (R + 255) / 256;
;   const int ntiles = TM * NT;
;   const int nb = gridDim.x;
;   const int xcd = blockIdx.x & 7, slot = blockIdx.x >> 3, per = nb >> 3;
;   for (int it = 0; it * nb < ntiles; ++it) {
;     const int k = (it * 8 + xcd) * per + slot;
;     if (k >= ntiles) continue;
;     const int panel = k / (TM * 8);
;     const int w = min(8, NT - panel * 8);
;     const int idx = k - panel * TM * 8;
;     const int tm = idx / w, tn = panel * 8 + idx % w;
;     gemm_tile8p<EPI>(A, Bt, K, K >> 6, tm * 256, tn * 256, smem, outp, ldo, nvalid, tm * 256, R - tm * 256);
;   }
.Lskew_done_g1:
	s_branch .LBB0_1062
.LBB0_1060:
	s_or_b64 exec, exec, s[2:3]
	s_waitcnt vmcnt(0)
	s_barrier
